# attention: second query sub-tile loads hoisted; unit epilogue stores widened to dwordx4 with v_permlane32_swap pairs (8 instead of 16 row-per-lane stores per wave)
# speedup vs baseline: 1.0193x; 1.0051x over previous
.LBB0_1166:
	v_readlane_b32 s12, v243, 21
	v_readlane_b32 s13, v243, 22
	v_readlane_b32 s16, v243, 25
	v_readlane_b32 s17, v243, 26
	v_readlane_b32 s20, v243, 29
	v_readlane_b32 s21, v243, 30
	v_ashrrev_i32_e32 v165, 31, v164
	s_mov_b64 s[12:13], s[16:17]
	s_mov_b64 s[16:17], s[20:21]
	v_lshl_add_u64 v[80:81], v[164:165], 2, s[16:17]
	v_mov_b32_e32 v80, v240
	ds_bpermute_b32 v82, v202, v188
	v_readlane_b32 s11, v243, 60
	v_readlane_b32 s6, v243, 50
	v_readlane_b32 s7, v243, 51
	v_readlane_b32 s14, v243, 23
	s_waitcnt lgkmcnt(0)
	v_add_f32_e32 v82, v188, v82
	v_readlane_b32 s15, v243, 24
	v_readlane_b32 s18, v243, 27
	v_readlane_b32 s19, v243, 28
	v_readlane_b32 s22, v243, 31
	v_readlane_b32 s23, v243, 32
	v_readlane_b32 s24, v243, 33
	v_readlane_b32 s25, v243, 34
	v_readlane_b32 s26, v243, 35
	v_readlane_b32 s27, v243, 36
	s_waitcnt vmcnt(0)
	v_fmamk_f32 v80, v80, 0x3fb8aa3b, v0
	v_exp_f32_e32 v83, v80
	v_lshl_add_u64 v[80:81], v[162:163], 1, v[154:155]
	v_add_f32_e32 v82, v83, v82
	v_div_scale_f32 v84, s[0:1], v82, v82, 1.0
	v_rcp_f32_e32 v85, v84
	s_nop 0
	v_fma_f32 v86, -v84, v85, 1.0
	v_fmac_f32_e32 v85, v86, v85
	v_div_scale_f32 v86, vcc, 1.0, v82, 1.0
	v_mul_f32_e32 v87, v86, v85
	v_fma_f32 v88, -v84, v87, v86
	v_fmac_f32_e32 v87, v88, v85
	v_fma_f32 v84, -v84, v87, v86
	v_div_fmas_f32 v84, v84, v85, v87
	v_div_fixup_f32 v82, v84, v82, 1.0
	v_lshlrev_b64 v[84:85], 11, v[160:161]
	v_lshl_add_u64 v[84:85], v[80:81], 0, v[84:85]
	v_and_b32_e32 v252, 32, v168
	v_lshrrev_b32_e32 v252, 2, v252
	v_mov_b32_e32 v253, 0
	v_lshl_add_u64 v[84:85], v[84:85], 0, v[252:253]
	v_pk_mul_f32 v[48:49], v[48:49], v[82:83] op_sel_hi:[1,0]
	v_pk_mul_f32 v[50:51], v[50:51], v[82:83] op_sel_hi:[1,0]
	v_pk_mul_f32 v[52:53], v[52:53], v[82:83] op_sel_hi:[1,0]
	v_pk_mul_f32 v[54:55], v[54:55], v[82:83] op_sel_hi:[1,0]
	v_cvt_pk_bf16_f32 v244, v48, v49
	v_cvt_pk_bf16_f32 v245, v50, v51
	v_cvt_pk_bf16_f32 v246, v52, v53
	v_cvt_pk_bf16_f32 v247, v54, v55
	s_nop 1
	v_permlane32_swap_b32_e32 v244, v246
	v_permlane32_swap_b32_e32 v245, v247
	global_store_dwordx4 v[84:85], v[244:247], off offset:64
	v_pk_mul_f32 v[56:57], v[56:57], v[82:83] op_sel_hi:[1,0]
	v_pk_mul_f32 v[58:59], v[58:59], v[82:83] op_sel_hi:[1,0]
	v_pk_mul_f32 v[60:61], v[60:61], v[82:83] op_sel_hi:[1,0]
	v_pk_mul_f32 v[62:63], v[62:63], v[82:83] op_sel_hi:[1,0]
	v_cvt_pk_bf16_f32 v248, v56, v57
	v_cvt_pk_bf16_f32 v249, v58, v59
	v_cvt_pk_bf16_f32 v250, v60, v61
	v_cvt_pk_bf16_f32 v251, v62, v63
	s_nop 1
	v_permlane32_swap_b32_e32 v248, v250
	v_permlane32_swap_b32_e32 v249, v251
	global_store_dwordx4 v[84:85], v[248:251], off offset:96
	ds_bpermute_b32 v48, v202, v187
	v_pk_mul_f32 v[64:65], v[64:65], v[82:83] op_sel_hi:[1,0]
	v_pk_mul_f32 v[66:67], v[66:67], v[82:83] op_sel_hi:[1,0]
	v_pk_mul_f32 v[68:69], v[68:69], v[82:83] op_sel_hi:[1,0]
	v_pk_mul_f32 v[70:71], v[70:71], v[82:83] op_sel_hi:[1,0]
	v_cvt_pk_bf16_f32 v244, v64, v65
	v_cvt_pk_bf16_f32 v245, v66, v67
	v_cvt_pk_bf16_f32 v246, v68, v69
	v_cvt_pk_bf16_f32 v247, v70, v71
	s_nop 1
	v_permlane32_swap_b32_e32 v244, v246
	v_permlane32_swap_b32_e32 v245, v247
	global_store_dwordx4 v[84:85], v[244:247], off
	v_pk_mul_f32 v[72:73], v[72:73], v[82:83] op_sel_hi:[1,0]
	v_pk_mul_f32 v[74:75], v[74:75], v[82:83] op_sel_hi:[1,0]
	v_pk_mul_f32 v[76:77], v[76:77], v[82:83] op_sel_hi:[1,0]
	v_pk_mul_f32 v[78:79], v[78:79], v[82:83] op_sel_hi:[1,0]
	v_cvt_pk_bf16_f32 v248, v72, v73
	v_cvt_pk_bf16_f32 v249, v74, v75
	v_cvt_pk_bf16_f32 v250, v76, v77
	v_cvt_pk_bf16_f32 v251, v78, v79
	s_nop 1
	v_permlane32_swap_b32_e32 v248, v250
	v_permlane32_swap_b32_e32 v249, v251
	global_store_dwordx4 v[84:85], v[248:251], off offset:32
	s_waitcnt lgkmcnt(0)
	v_add_f32_e32 v48, v187, v48
	v_add_f32_e32 v48, v83, v48
	v_div_scale_f32 v49, s[0:1], v48, v48, 1.0
	v_rcp_f32_e32 v50, v49
	s_nop 0
	v_fma_f32 v51, -v49, v50, 1.0
	v_fmac_f32_e32 v50, v51, v50
	v_div_scale_f32 v51, vcc, 1.0, v48, 1.0
	v_mul_f32_e32 v52, v51, v50
	v_fma_f32 v53, -v49, v52, v51
	v_fmac_f32_e32 v52, v53, v50
	v_fma_f32 v49, -v49, v52, v51
	v_div_fmas_f32 v49, v49, v50, v52
	v_div_fixup_f32 v48, v49, v48, 1.0
	v_lshlrev_b64 v[50:51], 11, v[166:167]
	v_lshl_add_u64 v[50:51], v[80:81], 0, v[50:51]
	v_lshl_add_u64 v[50:51], v[50:51], 0, v[252:253]
	v_pk_mul_f32 v[32:33], v[32:33], v[48:49] op_sel_hi:[1,0]
	v_pk_mul_f32 v[34:35], v[34:35], v[48:49] op_sel_hi:[1,0]
	v_pk_mul_f32 v[36:37], v[36:37], v[48:49] op_sel_hi:[1,0]
	v_pk_mul_f32 v[38:39], v[38:39], v[48:49] op_sel_hi:[1,0]
	v_cvt_pk_bf16_f32 v244, v32, v33
	v_cvt_pk_bf16_f32 v245, v34, v35
	v_cvt_pk_bf16_f32 v246, v36, v37
	v_cvt_pk_bf16_f32 v247, v38, v39
	s_nop 1
	v_permlane32_swap_b32_e32 v244, v246
	v_permlane32_swap_b32_e32 v245, v247
	global_store_dwordx4 v[50:51], v[244:247], off
	v_pk_mul_f32 v[40:41], v[40:41], v[48:49] op_sel_hi:[1,0]
	v_pk_mul_f32 v[42:43], v[42:43], v[48:49] op_sel_hi:[1,0]
	v_pk_mul_f32 v[44:45], v[44:45], v[48:49] op_sel_hi:[1,0]
	v_pk_mul_f32 v[46:47], v[46:47], v[48:49] op_sel_hi:[1,0]
	v_cvt_pk_bf16_f32 v248, v40, v41
	v_cvt_pk_bf16_f32 v249, v42, v43
	v_cvt_pk_bf16_f32 v250, v44, v45
	v_cvt_pk_bf16_f32 v251, v46, v47
	s_nop 1
	v_permlane32_swap_b32_e32 v248, v250
	v_permlane32_swap_b32_e32 v249, v251
	global_store_dwordx4 v[50:51], v[248:251], off offset:32
	v_pk_mul_f32 v[16:17], v[16:17], v[48:49] op_sel_hi:[1,0]
	v_pk_mul_f32 v[18:19], v[18:19], v[48:49] op_sel_hi:[1,0]
	v_pk_mul_f32 v[20:21], v[20:21], v[48:49] op_sel_hi:[1,0]
	v_pk_mul_f32 v[22:23], v[22:23], v[48:49] op_sel_hi:[1,0]
	v_cvt_pk_bf16_f32 v244, v16, v17
	v_cvt_pk_bf16_f32 v245, v18, v19
	v_cvt_pk_bf16_f32 v246, v20, v21
	v_cvt_pk_bf16_f32 v247, v22, v23
	s_nop 1
	v_permlane32_swap_b32_e32 v244, v246
	v_permlane32_swap_b32_e32 v245, v247
	global_store_dwordx4 v[50:51], v[244:247], off offset:64
	v_pk_mul_f32 v[24:25], v[24:25], v[48:49] op_sel_hi:[1,0]
	v_pk_mul_f32 v[26:27], v[26:27], v[48:49] op_sel_hi:[1,0]
	v_pk_mul_f32 v[28:29], v[28:29], v[48:49] op_sel_hi:[1,0]
	v_pk_mul_f32 v[30:31], v[30:31], v[48:49] op_sel_hi:[1,0]
	v_cvt_pk_bf16_f32 v248, v24, v25
	v_cvt_pk_bf16_f32 v249, v26, v27
	v_cvt_pk_bf16_f32 v250, v28, v29
	v_cvt_pk_bf16_f32 v251, v30, v31
	s_nop 1
	v_permlane32_swap_b32_e32 v248, v250
	v_permlane32_swap_b32_e32 v249, v251
	global_store_dwordx4 v[50:51], v[248:251], off offset:96
	v_readlane_b32 s0, v243, 1
	v_readlane_b32 s2, v243, 3
	s_nop 3
	s_add_i32 s11, s11, s2
	s_cmpk_gt_i32 s11, 0x7ff
	v_readlane_b32 s1, v243, 2
	v_readlane_b32 s3, v243, 4
	s_cbranch_scc1 .LBB0_1202
.LBB0_1167:
	s_bfe_u32 s70, s11, 0x20006
	s_lshl_b32 s71, s11, 7
	s_and_b32 s71, s71, 0x1f80
	s_lshl_b32 s72, s11, 5
	s_and_b32 s72, s72, 0xffffe000
	v_readlane_b32 s74, v243, 56
	v_readlane_b32 s75, v243, 57
	s_cmp_eq_u32 s71, 0
	s_cselect_b32 s73, 0, 0xffffff80
	s_or_b32 s72, s72, s71
	s_add_i32 s72, s72, s73
	s_lshl_b32 s70, s70, 7
	s_mov_b32 s71, 0
	s_movk_i32 s78, 0xc00
	v_add_u32_e32 v220, s72, v177
	v_mov_b64_e32 v[222:223], s[74:75]
	s_nop 0
	v_mad_i64_i32 v[220:221], s[76:77], v220, s78, v[222:223]
	v_lshl_add_u64 v[220:221], v[220:221], 0, s[70:71]
	v_lshl_add_u64 v[220:221], v[220:221], 0, v[144:145]
	global_load_dwordx4 v[204:207], v[220:221], off offset:2064
	global_load_dwordx4 v[208:211], v[220:221], off offset:2048
	global_load_dwordx4 v[212:215], v[220:221], off offset:2560
	global_load_dwordx4 v[216:219], v[220:221], off offset:2576
	s_bfe_u32 s1, s11, 0x20006
	s_lshl_b32 s0, s11, 7
	v_lshl_add_u32 v164, s1, 2, v175
	v_readlane_b32 s76, v243, 29
	v_readlane_b32 s77, v243, 30
	v_mov_b32_e32 v240, v164
	v_ashrrev_i32_e32 v241, 31, v164
	s_nop 1
	v_lshl_add_u64 v[240:241], v[240:241], 2, s[76:77]
	global_load_dword v240, v[240:241], off
	s_and_b32 s0, s0, 0x1f80
	s_lshl_b32 s2, s11, 5
	v_lshlrev_b32_e32 v162, 6, v164
	v_or_b32_e32 v18, s0, v176
	s_and_b32 s2, s2, 0xffffe000
	v_ashrrev_i32_e32 v163, 31, v162
	v_lshl_add_u64 v[64:65], v[162:163], 1, v[146:147]
	v_or3_b32 v160, s2, v149, v18
	s_movk_i32 s10, 0xc00
	v_mov_b32_e32 v16, v174
	v_lshrrev_b32_e32 v48, 6, v18
	v_mad_i64_i32 v[18:19], s[4:5], v160, s10, v[64:65]
	global_load_dwordx4 v[84:87], v[18:19], off
	global_load_dwordx4 v[88:91], v[18:19], off offset:32
	global_load_dwordx4 v[94:97], v[18:19], off offset:64
	global_load_dwordx4 v[98:101], v[18:19], off offset:96
	s_mov_b32 s98, 0x18000
	s_mov_b32 s99, 0
	v_lshl_add_u64 v[244:245], v[18:19], 0, s[98:99]
	global_load_dwordx4 v[224:227], v[244:245], off
	global_load_dwordx4 v[228:231], v[244:245], off offset:32
	global_load_dwordx4 v[232:235], v[244:245], off offset:64
	global_load_dwordx4 v[236:239], v[244:245], off offset:96
	v_lshlrev_b32_e32 v60, 3, v16
	v_ashrrev_i32_e32 v61, 31, v60
	v_lshl_add_u64 v[16:17], v[60:61], 2, s[12:13]
	global_load_dwordx4 v[44:47], v[16:17], off
	global_load_dwordx4 v[40:43], v[16:17], off offset:16
	global_load_dwordx4 v[36:39], v[16:17], off offset:64
	global_load_dwordx4 v[32:35], v[16:17], off offset:80
	v_cvt_f32_i32_e32 v18, v60
	v_or_b32_e32 v51, 2, v60
	v_cvt_f32_i32_e32 v51, v51
	v_cvt_f32_ubyte0_e32 v61, v48
	v_mul_f32_e32 v18, 0xbf549a78, v18
	v_exp_f32_e32 v49, v18
	global_load_dwordx4 v[28:31], v[16:17], off offset:128
	global_load_dwordx4 v[24:27], v[16:17], off offset:144
	global_load_dwordx4 v[20:23], v[16:17], off offset:192
	s_nop 0
	global_load_dwordx4 v[16:19], v[16:17], off offset:208
	v_mul_f32_e32 v51, 0xbf549a78, v51
	v_exp_f32_e32 v53, v51
	v_mul_f32_e32 v165, 0.15915494, v49
	v_or_b32_e32 v49, 1, v60
	v_cvt_f32_i32_e32 v49, v49
	v_or_b32_e32 v57, 5, v60
	v_cvt_f32_i32_e32 v57, v57
	v_mul_f32_e32 v171, 0.15915494, v53
	v_mul_f32_e32 v49, 0xbf549a78, v49
	v_exp_f32_e32 v49, v49
	v_mul_f32_e32 v53, v171, v61
	v_mul_f32_e32 v57, 0xbf549a78, v57
	v_or_b32_e32 v59, 6, v60
	v_mul_f32_e32 v170, 0.15915494, v49
	v_mul_f32_e32 v52, v170, v61
	v_cos_f32_e32 v49, v52
	v_sin_f32_e32 v51, v52
	v_or_b32_e32 v52, 3, v60
	v_cvt_f32_i32_e32 v54, v52
	v_cos_f32_e32 v52, v53
	v_exp_f32_e32 v57, v57
	v_cvt_f32_i32_e32 v59, v59
	v_mul_f32_e32 v54, 0xbf549a78, v54
	v_exp_f32_e32 v55, v54
	v_sin_f32_e32 v54, v53
	v_or_b32_e32 v53, 4, v60
	v_cvt_f32_i32_e32 v56, v53
	v_mul_f32_e32 v187, 0.15915494, v57
	v_mul_f32_e32 v57, 0xbf549a78, v59
	v_exp_f32_e32 v63, v57
	v_mul_f32_e32 v56, 0xbf549a78, v56
	v_exp_f32_e32 v56, v56
	v_or_b32_e32 v57, 7, v60
	v_cvt_f32_i32_e32 v60, v57
	v_mul_f32_e32 v50, v165, v61
	v_mul_f32_e32 v172, 0.15915494, v55
	v_cos_f32_e32 v48, v50
	v_sin_f32_e32 v50, v50
	v_mul_f32_e32 v55, v172, v61
	v_mul_f32_e32 v173, 0.15915494, v56
	v_cos_f32_e32 v53, v55
	v_sin_f32_e32 v55, v55
	v_mul_f32_e32 v58, v173, v61
	v_mul_f32_e32 v62, v187, v61
	v_cos_f32_e32 v56, v58
	v_sin_f32_e32 v58, v58
	v_cos_f32_e32 v57, v62
	v_sin_f32_e32 v59, v62
	v_mul_f32_e32 v60, 0xbf549a78, v60
	v_mul_f32_e32 v92, 0.15915494, v63
	v_exp_f32_e32 v63, v60
	v_or_b32_e32 v166, 32, v160
	v_mad_i64_i32 v[64:65], s[4:5], v166, s10, v[64:65]
	v_mul_f32_e32 v93, 0.15915494, v63
	v_mul_f32_e32 v62, v92, v61
	v_mul_f32_e32 v63, v93, v61
	v_cos_f32_e32 v60, v62
	v_cos_f32_e32 v61, v63
	v_sin_f32_e32 v62, v62
	v_sin_f32_e32 v63, v63
	v_mul_f32_e32 v67, v165, v181
	v_mul_f32_e32 v68, v170, v181
	v_cos_f32_e32 v66, v67
	v_sin_f32_e32 v70, v67
	s_waitcnt vmcnt(15)
	v_lshlrev_b32_e32 v140, 16, v84
	v_and_b32_e32 v141, 0xffff0000, v84
	v_lshlrev_b32_e32 v132, 16, v85
	v_and_b32_e32 v133, 0xffff0000, v85
	v_pk_mul_f32 v[84:85], v[140:141], v[140:141]
	v_pk_mul_f32 v[134:135], v[132:133], v[132:133]
	v_add_f32_e32 v84, v84, v85
	v_lshlrev_b32_e32 v128, 16, v86
	v_and_b32_e32 v129, 0xffff0000, v86
	v_add_f32_e32 v84, v134, v84
	v_lshlrev_b32_e32 v120, 16, v87
	v_and_b32_e32 v121, 0xffff0000, v87
	v_pk_mul_f32 v[86:87], v[128:129], v[128:129]
	v_add_f32_e32 v84, v135, v84
	v_add_f32_e32 v84, v86, v84
	v_pk_mul_f32 v[122:123], v[120:121], v[120:121]
	v_add_f32_e32 v84, v87, v84
	s_waitcnt vmcnt(14)
	v_lshlrev_b32_e32 v142, 16, v88
	v_and_b32_e32 v143, 0xffff0000, v88
	v_add_f32_e32 v84, v122, v84
	v_lshlrev_b32_e32 v136, 16, v89
	v_and_b32_e32 v137, 0xffff0000, v89
	v_pk_mul_f32 v[88:89], v[142:143], v[142:143]
	v_add_f32_e32 v84, v123, v84
	v_add_f32_e32 v84, v88, v84
	v_pk_mul_f32 v[138:139], v[136:137], v[136:137]
	v_add_f32_e32 v84, v89, v84
	v_lshlrev_b32_e32 v130, 16, v90
	v_and_b32_e32 v131, 0xffff0000, v90
	v_add_f32_e32 v84, v138, v84
	v_lshlrev_b32_e32 v124, 16, v91
	v_and_b32_e32 v125, 0xffff0000, v91
	v_pk_mul_f32 v[90:91], v[130:131], v[130:131]
	v_add_f32_e32 v84, v139, v84
	v_add_f32_e32 v84, v90, v84
	v_pk_mul_f32 v[126:127], v[124:125], v[124:125]
	v_add_f32_e32 v84, v91, v84
	s_waitcnt vmcnt(13)
	v_lshlrev_b32_e32 v114, 16, v94
	v_and_b32_e32 v115, 0xffff0000, v94
	v_add_f32_e32 v84, v126, v84
	v_lshlrev_b32_e32 v108, 16, v95
	v_and_b32_e32 v109, 0xffff0000, v95
	v_pk_mul_f32 v[94:95], v[114:115], v[114:115]
	v_add_f32_e32 v84, v127, v84
	v_add_f32_e32 v84, v94, v84
	v_pk_mul_f32 v[110:111], v[108:109], v[108:109]
	v_add_f32_e32 v84, v95, v84
	v_lshlrev_b32_e32 v106, 16, v96
	v_and_b32_e32 v107, 0xffff0000, v96
	v_add_f32_e32 v84, v110, v84
	v_lshlrev_b32_e32 v80, 16, v97
	v_and_b32_e32 v81, 0xffff0000, v97
	v_pk_mul_f32 v[96:97], v[106:107], v[106:107]
	v_add_f32_e32 v84, v111, v84
	v_add_f32_e32 v84, v96, v84
	v_pk_mul_f32 v[102:103], v[80:81], v[80:81]
	v_add_f32_e32 v84, v97, v84
	s_waitcnt vmcnt(12)
	v_lshlrev_b32_e32 v118, 16, v98
	v_and_b32_e32 v119, 0xffff0000, v98
	v_add_f32_e32 v84, v102, v84
	v_lshlrev_b32_e32 v116, 16, v99
	v_and_b32_e32 v117, 0xffff0000, v99
	v_pk_mul_f32 v[98:99], v[118:119], v[118:119]
	v_add_f32_e32 v84, v103, v84
	v_add_f32_e32 v84, v98, v84
	v_pk_mul_f32 v[112:113], v[116:117], v[116:117]
	v_add_f32_e32 v84, v99, v84
	v_lshlrev_b32_e32 v82, 16, v100
	v_and_b32_e32 v83, 0xffff0000, v100
	v_add_f32_e32 v84, v112, v84
	v_lshlrev_b32_e32 v78, 16, v101
	v_and_b32_e32 v79, 0xffff0000, v101
	v_pk_mul_f32 v[100:101], v[82:83], v[82:83]
	v_add_f32_e32 v84, v113, v84
	v_add_f32_e32 v84, v100, v84
	v_pk_mul_f32 v[104:105], v[78:79], v[78:79]
	v_add_f32_e32 v84, v101, v84
	v_add_f32_e32 v84, v104, v84
	v_add_f32_e32 v85, v105, v84
	ds_bpermute_b32 v87, v202, v85
	v_cos_f32_e32 v67, v68
	v_sin_f32_e32 v71, v68
	v_mul_f32_e32 v69, v171, v181
	v_mul_f32_e32 v72, v172, v181
	s_waitcnt lgkmcnt(0)
	v_add_f32_e32 v85, v85, v87
	v_fmamk_f32 v85, v85, 0x3c800000, v186
	v_rsq_f32_e32 v88, v85
	v_cos_f32_e32 v68, v69
	v_sin_f32_e32 v74, v69
	v_cos_f32_e32 v69, v72
	v_mul_f32_e32 v94, 0x3e38aa3b, v88
	s_waitcnt vmcnt(7)
	v_pk_mul_f32 v[88:89], v[44:45], v[94:95] op_sel_hi:[1,0]
	s_waitcnt vmcnt(1)
	v_pk_mul_f32 v[122:123], v[20:21], v[94:95] op_sel_hi:[1,0]
	v_pk_mul_f32 v[96:97], v[88:89], v[140:141]
	v_pk_mul_f32 v[88:89], v[46:47], v[94:95] op_sel_hi:[1,0]
	v_pk_mul_f32 v[112:113], v[26:27], v[94:95] op_sel_hi:[1,0]
	v_pk_mul_f32 v[98:99], v[88:89], v[132:133]
	v_pk_mul_f32 v[88:89], v[40:41], v[94:95] op_sel_hi:[1,0]
	v_pk_mul_f32 v[80:81], v[112:113], v[80:81]
	v_pk_mul_f32 v[100:101], v[88:89], v[128:129]
	v_pk_mul_f32 v[88:89], v[42:43], v[94:95] op_sel_hi:[1,0]
	v_pk_mul_f32 v[128:129], v[122:123], v[118:119]
	v_pk_mul_f32 v[102:103], v[88:89], v[120:121]
	v_pk_mul_f32 v[88:89], v[36:37], v[94:95] op_sel_hi:[1,0]
	v_pk_mul_f32 v[118:119], v[22:23], v[94:95] op_sel_hi:[1,0]
	v_pk_mul_f32 v[104:105], v[88:89], v[142:143]
	v_pk_mul_f32 v[88:89], v[38:39], v[94:95] op_sel_hi:[1,0]
	v_sin_f32_e32 v75, v72
	v_pk_mul_f32 v[110:111], v[88:89], v[136:137]
	v_pk_mul_f32 v[88:89], v[32:33], v[94:95] op_sel_hi:[1,0]
	v_mul_f32_e32 v73, v173, v181
	v_pk_mul_f32 v[120:121], v[88:89], v[130:131]
	v_pk_mul_f32 v[88:89], v[34:35], v[94:95] op_sel_hi:[1,0]
	v_pk_mul_f32 v[130:131], v[118:119], v[116:117]
	v_pk_mul_f32 v[124:125], v[88:89], v[124:125]
	v_pk_mul_f32 v[88:89], v[28:29], v[94:95] op_sel_hi:[1,0]
	s_waitcnt vmcnt(0)
	v_pk_mul_f32 v[116:117], v[16:17], v[94:95] op_sel_hi:[1,0]
	v_pk_mul_f32 v[126:127], v[88:89], v[114:115]
	v_pk_mul_f32 v[88:89], v[30:31], v[94:95] op_sel_hi:[1,0]
	v_pk_mul_f32 v[82:83], v[116:117], v[82:83]
	v_pk_mul_f32 v[108:109], v[88:89], v[108:109]
	v_pk_mul_f32 v[88:89], v[24:25], v[94:95] op_sel_hi:[1,0]
	v_pk_mul_f32 v[94:95], v[18:19], v[94:95] op_sel_hi:[1,0]
	v_pk_mul_f32 v[116:117], v[58:59], v[120:121]
	v_pk_mul_f32 v[78:79], v[94:95], v[78:79]
	v_pk_mul_f32 v[94:95], v[48:49], v[104:105]
	v_pk_mul_f32 v[104:105], v[50:51], v[104:105]
	v_pk_fma_f32 v[94:95], v[50:51], v[96:97], v[94:95]
	v_pk_fma_f32 v[96:97], v[48:49], v[96:97], v[104:105] neg_lo:[0,0,1] neg_hi:[0,0,1]
	v_pk_mul_f32 v[104:105], v[52:53], v[110:111]
	v_pk_mul_f32 v[110:111], v[54:55], v[110:111]
	v_pk_fma_f32 v[104:105], v[54:55], v[98:99], v[104:105]
	v_pk_fma_f32 v[98:99], v[52:53], v[98:99], v[110:111] neg_lo:[0,0,1] neg_hi:[0,0,1]
	v_pk_mul_f32 v[110:111], v[56:57], v[120:121]
	v_pk_mul_f32 v[120:121], v[60:61], v[124:125]
	v_pk_fma_f32 v[110:111], v[58:59], v[100:101], v[110:111]
	v_pk_fma_f32 v[100:101], v[56:57], v[100:101], v[116:117] neg_lo:[0,0,1] neg_hi:[0,0,1]
	v_mov_b32_e32 v116, v224
	v_mov_b32_e32 v117, v225
	v_mov_b32_e32 v118, v226
	v_mov_b32_e32 v119, v227
	v_pk_fma_f32 v[132:133], v[62:63], v[102:103], v[120:121]
	v_mov_b32_e32 v120, v228
	v_mov_b32_e32 v121, v229
	v_mov_b32_e32 v122, v230
	v_mov_b32_e32 v123, v231
	v_pk_mul_f32 v[106:107], v[88:89], v[106:107]
	v_mov_b32_e32 v88, v232
	v_mov_b32_e32 v89, v233
	v_mov_b32_e32 v90, v234
	v_mov_b32_e32 v91, v235
	v_mov_b32_e32 v112, v236
	v_mov_b32_e32 v113, v237
	v_mov_b32_e32 v114, v238
	v_mov_b32_e32 v115, v239
	v_pk_mul_f32 v[64:65], v[62:63], v[124:125]
	v_mul_f32_e32 v77, v187, v181
	v_pk_fma_f32 v[64:65], v[60:61], v[102:103], v[64:65] neg_lo:[0,0,1] neg_hi:[0,0,1]
	v_pk_mul_f32 v[102:103], v[66:67], v[128:129]
	v_cos_f32_e32 v72, v73
	v_pk_fma_f32 v[124:125], v[70:71], v[126:127], v[102:103]
	v_pk_mul_f32 v[70:71], v[70:71], v[128:129]
	v_sin_f32_e32 v76, v73
	v_pk_fma_f32 v[66:67], v[66:67], v[126:127], v[70:71] neg_lo:[0,0,1] neg_hi:[0,0,1]
	v_pk_mul_f32 v[70:71], v[68:69], v[130:131]
	v_cos_f32_e32 v73, v77
	v_pk_fma_f32 v[70:71], v[74:75], v[108:109], v[70:71]
	v_pk_mul_f32 v[74:75], v[74:75], v[130:131]
	v_sin_f32_e32 v77, v77
	v_pk_fma_f32 v[68:69], v[68:69], v[108:109], v[74:75] neg_lo:[0,0,1] neg_hi:[0,0,1]
	v_cvt_pk_bf16_f32 v109, v70, v71
	v_mul_f32_e32 v70, v172, v182
	v_mul_f32_e32 v71, v173, v182
	v_mul_f32_e32 v86, v92, v181
	v_mul_f32_e32 v87, v93, v181
	v_cos_f32_e32 v84, v86
	v_sin_f32_e32 v86, v86
	v_cos_f32_e32 v85, v87
	v_sin_f32_e32 v87, v87
	v_pk_mul_f32 v[74:75], v[72:73], v[82:83]
	v_cvt_pk_bf16_f32 v96, v96, v97
	v_cvt_pk_bf16_f32 v97, v98, v99
	v_cvt_pk_bf16_f32 v98, v100, v101
	v_cvt_pk_bf16_f32 v101, v104, v105
	v_cvt_pk_bf16_f32 v104, v66, v67
	v_mul_f32_e32 v66, v170, v182
	v_mul_f32_e32 v67, v171, v182
	v_pk_fma_f32 v[74:75], v[76:77], v[106:107], v[74:75]
	v_pk_mul_f32 v[76:77], v[76:77], v[82:83]
	v_cvt_pk_bf16_f32 v103, v132, v133
	v_pk_fma_f32 v[72:73], v[72:73], v[106:107], v[76:77] neg_lo:[0,0,1] neg_hi:[0,0,1]
	v_pk_mul_f32 v[76:77], v[84:85], v[78:79]
	v_pk_mul_f32 v[78:79], v[86:87], v[78:79]
	v_pk_fma_f32 v[76:77], v[86:87], v[80:81], v[76:77]
	v_pk_fma_f32 v[78:79], v[84:85], v[80:81], v[78:79] neg_lo:[0,0,1] neg_hi:[0,0,1]
	v_cvt_pk_bf16_f32 v100, v94, v95
	v_cvt_pk_bf16_f32 v107, v78, v79
	v_cvt_pk_bf16_f32 v102, v110, v111
	v_cvt_pk_bf16_f32 v111, v76, v77
	v_cvt_pk_bf16_f32 v108, v124, v125
	s_cmp_eq_u32 s0, 0
	s_cselect_b64 s[4:5], -1, 0
	v_cvt_pk_bf16_f32 v99, v64, v65
	v_mul_f32_e32 v65, v165, v182
	v_cndmask_b32_e64 v165, 0, 1, s[4:5]
	s_and_b64 s[4:5], s[4:5], exec
	s_cselect_b32 s3, 0, 0xffffff80
	s_or_b32 s24, s2, s0
	s_add_i32 s4, s3, s24
	v_readlane_b32 s2, v243, 56
	v_readlane_b32 s3, v243, 57
	s_lshl_b32 s6, s1, 7
	s_barrier
	v_cvt_pk_bf16_f32 v105, v68, v69
	v_cos_f32_e32 v64, v65
	v_sin_f32_e32 v68, v65
	v_cos_f32_e32 v65, v66
	v_sin_f32_e32 v69, v66
	v_cvt_pk_bf16_f32 v106, v72, v73
	v_cvt_pk_bf16_f32 v110, v74, v75
	v_cos_f32_e32 v66, v67
	v_sin_f32_e32 v72, v67
	v_cos_f32_e32 v67, v70
	v_sin_f32_e32 v73, v70
	v_mul_f32_e32 v75, v187, v182
	v_cos_f32_e32 v70, v71
	v_sin_f32_e32 v74, v71
	s_waitcnt vmcnt(3)
	v_lshlrev_b32_e32 v194, 16, v116
	v_and_b32_e32 v195, 0xffff0000, v116
	v_lshlrev_b32_e32 v172, 16, v117
	v_and_b32_e32 v173, 0xffff0000, v117
	v_pk_mul_f32 v[116:117], v[194:195], v[194:195]
	v_pk_mul_f32 v[188:189], v[172:173], v[172:173]
	v_add_f32_e32 v116, v116, v117
	v_lshlrev_b32_e32 v142, 16, v118
	v_and_b32_e32 v143, 0xffff0000, v118
	v_add_f32_e32 v116, v188, v116
	v_lshlrev_b32_e32 v134, 16, v119
	v_and_b32_e32 v135, 0xffff0000, v119
	v_pk_mul_f32 v[118:119], v[142:143], v[142:143]
	v_add_f32_e32 v116, v189, v116
	v_add_f32_e32 v116, v118, v116
	v_pk_mul_f32 v[136:137], v[134:135], v[134:135]
	v_add_f32_e32 v116, v119, v116
	s_waitcnt vmcnt(2)
	v_lshlrev_b32_e32 v196, 16, v120
	v_and_b32_e32 v197, 0xffff0000, v120
	v_add_f32_e32 v116, v136, v116
	v_lshlrev_b32_e32 v190, 16, v121
	v_and_b32_e32 v191, 0xffff0000, v121
	v_pk_mul_f32 v[120:121], v[196:197], v[196:197]
	v_add_f32_e32 v116, v137, v116
	v_add_f32_e32 v116, v120, v116
	v_pk_mul_f32 v[192:193], v[190:191], v[190:191]
	v_add_f32_e32 v116, v121, v116
	v_lshlrev_b32_e32 v170, 16, v122
	v_and_b32_e32 v171, 0xffff0000, v122
	v_add_f32_e32 v116, v192, v116
	v_lshlrev_b32_e32 v138, 16, v123
	v_and_b32_e32 v139, 0xffff0000, v123
	v_pk_mul_f32 v[122:123], v[170:171], v[170:171]
	v_add_f32_e32 v116, v193, v116
	v_add_f32_e32 v116, v122, v116
	v_pk_mul_f32 v[140:141], v[138:139], v[138:139]
	v_add_f32_e32 v116, v123, v116
	s_waitcnt vmcnt(1)
	v_lshlrev_b32_e32 v78, 16, v91
	v_and_b32_e32 v79, 0xffff0000, v91
	v_lshlrev_b32_e32 v82, 16, v90
	v_and_b32_e32 v83, 0xffff0000, v90
	v_lshlrev_b32_e32 v90, 16, v88
	v_and_b32_e32 v91, 0xffff0000, v88
	v_add_f32_e32 v116, v140, v116
	v_pk_mul_f32 v[132:133], v[90:91], v[90:91]
	v_add_f32_e32 v116, v141, v116
	v_lshlrev_b32_e32 v86, 16, v89
	v_and_b32_e32 v87, 0xffff0000, v89
	v_add_f32_e32 v116, v132, v116
	v_pk_mul_f32 v[128:129], v[86:87], v[86:87]
	v_add_f32_e32 v116, v133, v116
	v_add_f32_e32 v116, v128, v116
	v_pk_mul_f32 v[126:127], v[82:83], v[82:83]
	v_add_f32_e32 v116, v129, v116
	v_add_f32_e32 v116, v126, v116
	v_pk_mul_f32 v[94:95], v[78:79], v[78:79]
	v_add_f32_e32 v116, v127, v116
	s_waitcnt vmcnt(0)
	v_lshlrev_b32_e32 v88, 16, v112
	v_and_b32_e32 v89, 0xffff0000, v112
	v_add_f32_e32 v94, v94, v116
	v_lshlrev_b32_e32 v84, 16, v113
	v_and_b32_e32 v85, 0xffff0000, v113
	v_pk_mul_f32 v[112:113], v[88:89], v[88:89]
	v_add_f32_e32 v94, v95, v94
	v_add_f32_e32 v94, v112, v94
	v_pk_mul_f32 v[130:131], v[84:85], v[84:85]
	v_add_f32_e32 v94, v113, v94
	v_lshlrev_b32_e32 v80, 16, v114
	v_and_b32_e32 v81, 0xffff0000, v114
	v_add_f32_e32 v94, v130, v94
	v_lshlrev_b32_e32 v76, 16, v115
	v_and_b32_e32 v77, 0xffff0000, v115
	v_pk_mul_f32 v[114:115], v[80:81], v[80:81]
	v_add_f32_e32 v94, v131, v94
	v_add_f32_e32 v94, v114, v94
	v_pk_mul_f32 v[124:125], v[76:77], v[76:77]
	v_add_f32_e32 v94, v115, v94
	v_add_f32_e32 v94, v124, v94
	v_add_f32_e32 v95, v125, v94
	ds_bpermute_b32 v112, v202, v95
	v_mov_b64_e32 v[120:121], s[2:3]
	v_or_b32_e32 v122, s4, v148
	v_cos_f32_e32 v71, v75
	v_sin_f32_e32 v75, v75
	s_waitcnt lgkmcnt(0)
	v_add_f32_e32 v95, v95, v112
	v_fmamk_f32 v95, v95, 0x3c800000, v186
	v_rsq_f32_e32 v112, v95
	v_mul_f32_e32 v94, v92, v182
	v_mul_f32_e32 v95, v93, v182
	v_cos_f32_e32 v92, v94
	v_mul_f32_e32 v128, 0x3e38aa3b, v112
	v_add_u32_e32 v112, s4, v177
	v_mad_i64_i32 v[112:113], s[2:3], v112, s10, v[120:121]
	v_mad_i64_i32 v[120:121], s[2:3], v122, s10, v[120:121]
	v_lshl_add_u64 v[112:113], v[112:113], 0, s[6:7]
	v_lshl_add_u64 v[120:121], v[120:121], 0, s[6:7]
	v_lshl_add_u64 v[116:117], v[112:113], 0, v[144:145]
	v_lshl_add_u64 v[124:125], v[112:113], 0, v[144:145]
	s_nop 0
	s_nop 0
	s_nop 0
	v_pk_mul_f32 v[36:37], v[36:37], v[128:129] op_sel_hi:[1,0]
	s_nop 0
	v_pk_mul_f32 v[44:45], v[44:45], v[128:129] op_sel_hi:[1,0]
	s_nop 0
	v_pk_mul_f32 v[36:37], v[36:37], v[196:197]
	v_pk_mul_f32 v[38:39], v[38:39], v[128:129] op_sel_hi:[1,0]
	v_pk_mul_f32 v[18:19], v[18:19], v[128:129] op_sel_hi:[1,0]
	v_pk_mul_f32 v[44:45], v[44:45], v[194:195]
	v_pk_mul_f32 v[46:47], v[46:47], v[128:129] op_sel_hi:[1,0]
	v_pk_mul_f32 v[38:39], v[38:39], v[190:191]
	v_pk_mul_f32 v[32:33], v[32:33], v[128:129] op_sel_hi:[1,0]
	v_pk_mul_f32 v[18:19], v[18:19], v[76:77]
	v_pk_mul_f32 v[76:77], v[48:49], v[36:37]
	v_pk_mul_f32 v[36:37], v[50:51], v[36:37]
	v_pk_mul_f32 v[46:47], v[46:47], v[172:173]
	v_pk_mul_f32 v[40:41], v[40:41], v[128:129] op_sel_hi:[1,0]
	v_pk_mul_f32 v[32:33], v[32:33], v[170:171]
	v_pk_mul_f32 v[34:35], v[34:35], v[128:129] op_sel_hi:[1,0]
	v_pk_fma_f32 v[76:77], v[50:51], v[44:45], v[76:77]
	v_pk_fma_f32 v[36:37], v[48:49], v[44:45], v[36:37] neg_lo:[0,0,1] neg_hi:[0,0,1]
	v_pk_mul_f32 v[44:45], v[52:53], v[38:39]
	v_pk_mul_f32 v[38:39], v[54:55], v[38:39]
	v_pk_mul_f32 v[40:41], v[40:41], v[142:143]
	v_pk_mul_f32 v[42:43], v[42:43], v[128:129] op_sel_hi:[1,0]
	v_pk_mul_f32 v[34:35], v[34:35], v[138:139]
	v_pk_mul_f32 v[20:21], v[20:21], v[128:129] op_sel_hi:[1,0]
	v_pk_fma_f32 v[44:45], v[54:55], v[46:47], v[44:45]
	v_pk_fma_f32 v[38:39], v[52:53], v[46:47], v[38:39] neg_lo:[0,0,1] neg_hi:[0,0,1]
	v_pk_mul_f32 v[46:47], v[56:57], v[32:33]
	v_pk_mul_f32 v[32:33], v[58:59], v[32:33]
	v_sin_f32_e32 v94, v94
	v_cos_f32_e32 v93, v95
	v_sin_f32_e32 v95, v95
	v_pk_mul_f32 v[42:43], v[42:43], v[134:135]
	v_pk_mul_f32 v[28:29], v[28:29], v[128:129] op_sel_hi:[1,0]
	v_pk_mul_f32 v[20:21], v[20:21], v[88:89]
	v_pk_mul_f32 v[22:23], v[22:23], v[128:129] op_sel_hi:[1,0]
	v_pk_fma_f32 v[46:47], v[58:59], v[40:41], v[46:47]
	v_pk_fma_f32 v[32:33], v[56:57], v[40:41], v[32:33] neg_lo:[0,0,1] neg_hi:[0,0,1]
	v_pk_mul_f32 v[40:41], v[60:61], v[34:35]
	v_pk_mul_f32 v[34:35], v[62:63], v[34:35]
	v_pk_mul_f32 v[28:29], v[28:29], v[90:91]
	v_pk_mul_f32 v[30:31], v[30:31], v[128:129] op_sel_hi:[1,0]
	v_pk_mul_f32 v[22:23], v[22:23], v[84:85]
	v_pk_mul_f32 v[16:17], v[16:17], v[128:129] op_sel_hi:[1,0]
	v_pk_fma_f32 v[40:41], v[62:63], v[42:43], v[40:41]
	v_pk_fma_f32 v[34:35], v[60:61], v[42:43], v[34:35] neg_lo:[0,0,1] neg_hi:[0,0,1]
	v_pk_mul_f32 v[42:43], v[64:65], v[20:21]
	v_pk_mul_f32 v[20:21], v[68:69], v[20:21]
	v_pk_mul_f32 v[30:31], v[30:31], v[86:87]
	v_pk_mul_f32 v[24:25], v[24:25], v[128:129] op_sel_hi:[1,0]
	v_pk_mul_f32 v[16:17], v[16:17], v[80:81]
	v_pk_fma_f32 v[42:43], v[68:69], v[28:29], v[42:43]
	v_pk_fma_f32 v[20:21], v[64:65], v[28:29], v[20:21] neg_lo:[0,0,1] neg_hi:[0,0,1]
	v_pk_mul_f32 v[28:29], v[66:67], v[22:23]
	v_pk_mul_f32 v[22:23], v[72:73], v[22:23]
	v_pk_mul_f32 v[24:25], v[24:25], v[82:83]
	v_pk_mul_f32 v[26:27], v[26:27], v[128:129] op_sel_hi:[1,0]
	v_pk_fma_f32 v[28:29], v[72:73], v[30:31], v[28:29]
	v_pk_fma_f32 v[22:23], v[66:67], v[30:31], v[22:23] neg_lo:[0,0,1] neg_hi:[0,0,1]
	v_pk_mul_f32 v[30:31], v[70:71], v[16:17]
	v_pk_mul_f32 v[16:17], v[74:75], v[16:17]
	v_pk_mul_f32 v[26:27], v[26:27], v[78:79]
	v_pk_fma_f32 v[30:31], v[74:75], v[24:25], v[30:31]
	v_pk_fma_f32 v[16:17], v[70:71], v[24:25], v[16:17] neg_lo:[0,0,1] neg_hi:[0,0,1]
	v_pk_mul_f32 v[24:25], v[92:93], v[18:19]
	v_pk_mul_f32 v[18:19], v[94:95], v[18:19]
	v_pk_fma_f32 v[24:25], v[94:95], v[26:27], v[24:25]
	v_pk_fma_f32 v[18:19], v[92:93], v[26:27], v[18:19] neg_lo:[0,0,1] neg_hi:[0,0,1]
	v_cvt_pk_bf16_f32 v142, v30, v31
	s_cmpk_eq_i32 s0, 0x1f80
	v_mov_b32_e32 v30, v145
	v_mov_b32_e32 v31, v145
	v_cvt_pk_bf16_f32 v128, v36, v37
	v_cvt_pk_bf16_f32 v129, v38, v39
	v_cvt_pk_bf16_f32 v130, v32, v33
	v_cvt_pk_bf16_f32 v131, v34, v35
	v_cvt_pk_bf16_f32 v132, v76, v77
	v_cvt_pk_bf16_f32 v133, v44, v45
	v_cvt_pk_bf16_f32 v134, v46, v47
	v_cvt_pk_bf16_f32 v135, v40, v41
	v_cvt_pk_bf16_f32 v136, v20, v21
	v_cvt_pk_bf16_f32 v137, v22, v23
	v_cvt_pk_bf16_f32 v138, v16, v17
	v_cvt_pk_bf16_f32 v139, v18, v19
	v_cvt_pk_bf16_f32 v140, v42, v43
	v_cvt_pk_bf16_f32 v141, v28, v29
	v_cvt_pk_bf16_f32 v143, v24, v25
	s_cselect_b32 s22, 3, 2
	v_writelane_b32 v243, s11, 60
	s_and_b32 s23, s11, 0xffffff00
	s_mov_b32 s1, s7
	v_mov_b32_e32 v16, v145
	v_mov_b32_e32 v17, v145
	v_mov_b32_e32 v18, v145
	v_mov_b32_e32 v19, v145
	v_mov_b32_e32 v20, v145
	v_mov_b32_e32 v21, v145
	v_mov_b32_e32 v22, v145
	v_mov_b32_e32 v23, v145
	v_mov_b32_e32 v24, v145
	v_mov_b32_e32 v25, v145
	v_mov_b32_e32 v26, v145
	v_mov_b32_e32 v27, v145
	v_mov_b32_e32 v28, v145
	v_mov_b32_e32 v29, v145
	v_mov_b64_e32 v[46:47], v[30:31]
	v_mov_b64_e32 v[62:63], v[30:31]
	v_mov_b64_e32 v[78:79], v[30:31]
	v_ashrrev_i32_e32 v161, 31, v160
	v_ashrrev_i32_e32 v167, 31, v166
	s_mov_b32 s33, 0
	v_readfirstlane_b32 s25, v165
	s_add_i32 s23, s23, 0xfe80
	s_addk_i32 s24, 0xff80
	v_lshl_add_u64 v[170:171], v[156:157], 0, s[6:7]
	v_writelane_b32 v243, s0, 50
	v_lshl_add_u64 v[172:173], v[158:159], 0, s[6:7]
	v_mov_b64_e32 v[44:45], v[28:29]
	v_mov_b64_e32 v[42:43], v[26:27]
	v_mov_b64_e32 v[40:41], v[24:25]
	v_mov_b64_e32 v[38:39], v[22:23]
	v_mov_b64_e32 v[36:37], v[20:21]
	v_mov_b64_e32 v[34:35], v[18:19]
	v_mov_b64_e32 v[32:33], v[16:17]
	v_mov_b64_e32 v[60:61], v[28:29]
	v_mov_b64_e32 v[58:59], v[26:27]
	v_mov_b64_e32 v[56:57], v[24:25]
	v_mov_b64_e32 v[54:55], v[22:23]
	v_mov_b64_e32 v[52:53], v[20:21]
	v_mov_b64_e32 v[50:51], v[18:19]
	v_mov_b64_e32 v[48:49], v[16:17]
	v_mov_b64_e32 v[76:77], v[28:29]
	v_mov_b64_e32 v[74:75], v[26:27]
	v_mov_b64_e32 v[72:73], v[24:25]
	v_mov_b64_e32 v[70:71], v[22:23]
	v_mov_b64_e32 v[68:69], v[20:21]
	v_mov_b64_e32 v[66:67], v[18:19]
	v_mov_b64_e32 v[64:65], v[16:17]
	v_mov_b32_e32 v187, 0
	v_mov_b32_e32 v188, 0
	s_waitcnt vmcnt(2)
	ds_write_b128 v179, v[208:211]
	ds_write_b128 v179, v[204:207] offset:16
	s_waitcnt vmcnt(1)
	ds_write_b16 v153, v212 offset:18432
	ds_write_b16_d16_hi v153, v212 offset:18696
	ds_write_b16 v153, v213 offset:18960
	ds_write_b16_d16_hi v153, v213 offset:19224
	ds_write_b16 v153, v214 offset:19488
	ds_write_b16_d16_hi v153, v214 offset:19752
	ds_write_b16 v153, v215 offset:20016
	ds_write_b16_d16_hi v153, v215 offset:20280
	s_waitcnt vmcnt(0)
	ds_write_b16 v153, v216 offset:20544
	ds_write_b16_d16_hi v153, v216 offset:20808
	ds_write_b16 v153, v217 offset:21072
	ds_write_b16_d16_hi v153, v217 offset:21336
	ds_write_b16 v153, v218 offset:21600
	ds_write_b16_d16_hi v153, v218 offset:21864
	ds_write_b16 v153, v219 offset:22128
	ds_write_b16_d16_hi v153, v219 offset:22392
	s_waitcnt lgkmcnt(0)
	s_barrier
	v_writelane_b32 v243, s1, 51
